# split-K tail epilogue (WO, down): 16x16 blocks transposed through LDS so each f32 atomic covers 4 rows x 64 B contiguous (4 requests instead of 16)
# speedup vs baseline: 1.0187x; 1.0187x over previous
;     __device__ __forceinline__ void operator()(const f32x4 (&acc)[2][2][4][2], const Unit& u, int wr, int wc, int fr, int fq) const {
;     ...
;         } else if (wr == 0) {
; #pragma unroll
;             for (int m = 0; m < 4; ++m) {
;                 const int t = m * 16 + fr;
;                 float* rp = (m < 2 ? dout + (size_t)(ROW_SAMPLE + t) * D : xmeta + (size_t)(t - 32) * D) + col0;
; #pragma unroll
;                 for (int bj = 0; bj < 2; ++bj)
; #pragma unroll
;                     for (int n = 0; n < 2; ++n) { const f32x4 v = acc[0][bj][m][n] * sc[bj][n]; float* p = rp + bj * HALF + n * 16;
;                         if (atomic_tail) { unsafeAtomicAdd(p + 0, v[0]); unsafeAtomicAdd(p + 1, v[1]); unsafeAtomicAdd(p + 2, v[2]); unsafeAtomicAdd(p + 3, v[3]); }
;                         else { const f32x4 x = *(const f32x4*)p; *(f32x4*)p = x + v; } }
;                 asm volatile("" ::: "memory");
;             }
.LBB0_1395:
	s_andn2_b64 vcc, exec, s[6:7]
	s_cbranch_vccnz .LBB0_1397
	v_lshlrev_b64 v[130:131], 2, v[160:161]
	v_and_b32_e32 v57, 63, v1
	v_lshrrev_b32_e32 v56, 6, v1
	v_and_b32_e32 v55, 15, v57
	v_lshrrev_b32_e32 v54, 4, v57
	v_lshlrev_b32_e32 v53, 6, v55
	v_lshl_add_u32 v53, v54, 4, v53
	v_lshlrev_b32_e32 v52, 10, v56
	v_add_u32_e32 v52, 0x23000, v52
	v_add_u32_e32 v53, v53, v52
	v_lshl_add_u32 v51, v57, 2, v52
	v_sub_u32_e32 v50, v54, v55
	v_lshlrev_b32_e32 v50, 13, v50
	v_lshl_add_u32 v50, v55, 2, v50
	v_lshlrev_b32_e32 v49, 4, v54
	v_sub_u32_e32 v2, v50, v49
	v_add_u32_e32 v4, 0x8000, v2
	v_add_u32_e32 v6, 0x10000, v2
	v_add_u32_e32 v8, 0x18000, v2
	v_ashrrev_i32_e32 v3, 31, v2
	v_ashrrev_i32_e32 v5, 31, v4
	v_ashrrev_i32_e32 v7, 31, v6
	v_ashrrev_i32_e32 v9, 31, v8
	v_lshl_add_u64 v[10:11], v[148:149], 0, v[130:131]
	v_lshl_add_u64 v[12:13], v[10:11], 0, v[2:3]
	v_lshl_add_u64 v[14:15], v[10:11], 0, v[4:5]
	v_lshl_add_u64 v[16:17], v[10:11], 0, v[6:7]
	v_lshl_add_u64 v[18:19], v[10:11], 0, v[8:9]
	ds_write_b128 v53, v[126:129]
	ds_read_b32 v65, v51
	ds_read_b32 v64, v51 offset:256
	ds_read_b32 v63, v51 offset:512
	ds_read_b32 v62, v51 offset:768
	s_waitcnt lgkmcnt(0)
	global_atomic_add_f32 v[12:13], v65, off
	global_atomic_add_f32 v[14:15], v64, off
	global_atomic_add_f32 v[16:17], v63, off
	global_atomic_add_f32 v[18:19], v62, off
	ds_write_b128 v53, v[122:125]
	ds_read_b32 v61, v51
	ds_read_b32 v60, v51 offset:256
	ds_read_b32 v59, v51 offset:512
	ds_read_b32 v58, v51 offset:768
	s_waitcnt lgkmcnt(0)
	global_atomic_add_f32 v[12:13], v61, off offset:64
	global_atomic_add_f32 v[14:15], v60, off offset:64
	global_atomic_add_f32 v[16:17], v59, off offset:64
	global_atomic_add_f32 v[18:19], v58, off offset:64
	ds_write_b128 v53, v[118:121]
	ds_read_b32 v65, v51
	ds_read_b32 v64, v51 offset:256
	ds_read_b32 v63, v51 offset:512
	ds_read_b32 v62, v51 offset:768
	s_waitcnt lgkmcnt(0)
	global_atomic_add_f32 v[12:13], v65, off offset:512
	global_atomic_add_f32 v[14:15], v64, off offset:512
	global_atomic_add_f32 v[16:17], v63, off offset:512
	global_atomic_add_f32 v[18:19], v62, off offset:512
	ds_write_b128 v53, v[114:117]
	ds_read_b32 v61, v51
	ds_read_b32 v60, v51 offset:256
	ds_read_b32 v59, v51 offset:512
	ds_read_b32 v58, v51 offset:768
	s_waitcnt lgkmcnt(0)
	global_atomic_add_f32 v[12:13], v61, off offset:576
	global_atomic_add_f32 v[14:15], v60, off offset:576
	global_atomic_add_f32 v[16:17], v59, off offset:576
	global_atomic_add_f32 v[18:19], v58, off offset:576
	v_lshl_add_u64 v[10:11], v[150:151], 0, v[130:131]
	v_lshl_add_u64 v[12:13], v[10:11], 0, v[2:3]
	v_lshl_add_u64 v[14:15], v[10:11], 0, v[4:5]
	v_lshl_add_u64 v[16:17], v[10:11], 0, v[6:7]
	v_lshl_add_u64 v[18:19], v[10:11], 0, v[8:9]
	ds_write_b128 v53, v[110:113]
	ds_read_b32 v65, v51
	ds_read_b32 v64, v51 offset:256
	ds_read_b32 v63, v51 offset:512
	ds_read_b32 v62, v51 offset:768
	s_waitcnt lgkmcnt(0)
	global_atomic_add_f32 v[12:13], v65, off
	global_atomic_add_f32 v[14:15], v64, off
	global_atomic_add_f32 v[16:17], v63, off
	global_atomic_add_f32 v[18:19], v62, off
	ds_write_b128 v53, v[106:109]
	ds_read_b32 v61, v51
	ds_read_b32 v60, v51 offset:256
	ds_read_b32 v59, v51 offset:512
	ds_read_b32 v58, v51 offset:768
	s_waitcnt lgkmcnt(0)
	global_atomic_add_f32 v[12:13], v61, off offset:64
	global_atomic_add_f32 v[14:15], v60, off offset:64
	global_atomic_add_f32 v[16:17], v59, off offset:64
	global_atomic_add_f32 v[18:19], v58, off offset:64
	ds_write_b128 v53, v[102:105]
	ds_read_b32 v65, v51
	ds_read_b32 v64, v51 offset:256
	ds_read_b32 v63, v51 offset:512
	ds_read_b32 v62, v51 offset:768
	s_waitcnt lgkmcnt(0)
	global_atomic_add_f32 v[12:13], v65, off offset:512
	global_atomic_add_f32 v[14:15], v64, off offset:512
	global_atomic_add_f32 v[16:17], v63, off offset:512
	global_atomic_add_f32 v[18:19], v62, off offset:512
	ds_write_b128 v53, v[98:101]
	ds_read_b32 v61, v51
	ds_read_b32 v60, v51 offset:256
	ds_read_b32 v59, v51 offset:512
	ds_read_b32 v58, v51 offset:768
	s_waitcnt lgkmcnt(0)
;     __device__ __forceinline__ void operator()(const f32x4 (&acc)[2][2][4][2], const Unit& u, int wr, int wc, int fr, int fq) const {
;     ...
;             for (int m = 0; m < 4; ++m) {
;                 const int t = m * 16 + fr;
;                 float* rp = (m < 2 ? dout + (size_t)(ROW_SAMPLE + t) * D : xmeta + (size_t)(t - 32) * D) + col0;
; #pragma unroll
;                 for (int bj = 0; bj < 2; ++bj)
; #pragma unroll
;                     for (int n = 0; n < 2; ++n) { const f32x4 v = acc[0][bj][m][n] * sc[bj][n]; float* p = rp + bj * HALF + n * 16;
;                         if (atomic_tail) { unsafeAtomicAdd(p + 0, v[0]); unsafeAtomicAdd(p + 1, v[1]); unsafeAtomicAdd(p + 2, v[2]); unsafeAtomicAdd(p + 3, v[3]); }
;                         else { const f32x4 x = *(const f32x4*)p; *(f32x4*)p = x + v; } }
;                 asm volatile("" ::: "memory");
	global_atomic_add_f32 v[12:13], v61, off offset:576
	global_atomic_add_f32 v[14:15], v60, off offset:576
	global_atomic_add_f32 v[16:17], v59, off offset:576
	global_atomic_add_f32 v[18:19], v58, off offset:576
	v_lshl_add_u64 v[10:11], v[152:153], 0, v[130:131]
	v_lshl_add_u64 v[12:13], v[10:11], 0, v[2:3]
	v_lshl_add_u64 v[14:15], v[10:11], 0, v[4:5]
	v_lshl_add_u64 v[16:17], v[10:11], 0, v[6:7]
	v_lshl_add_u64 v[18:19], v[10:11], 0, v[8:9]
	ds_write_b128 v53, v[94:97]
	ds_read_b32 v65, v51
	ds_read_b32 v64, v51 offset:256
	ds_read_b32 v63, v51 offset:512
	ds_read_b32 v62, v51 offset:768
	s_waitcnt lgkmcnt(0)
	global_atomic_add_f32 v[12:13], v65, off
	global_atomic_add_f32 v[14:15], v64, off
	global_atomic_add_f32 v[16:17], v63, off
	global_atomic_add_f32 v[18:19], v62, off
	ds_write_b128 v53, v[90:93]
	ds_read_b32 v61, v51
	ds_read_b32 v60, v51 offset:256
	ds_read_b32 v59, v51 offset:512
	ds_read_b32 v58, v51 offset:768
	s_waitcnt lgkmcnt(0)
	global_atomic_add_f32 v[12:13], v61, off offset:64
	global_atomic_add_f32 v[14:15], v60, off offset:64
	global_atomic_add_f32 v[16:17], v59, off offset:64
	global_atomic_add_f32 v[18:19], v58, off offset:64
	ds_write_b128 v53, v[86:89]
	ds_read_b32 v65, v51
	ds_read_b32 v64, v51 offset:256
	ds_read_b32 v63, v51 offset:512
	ds_read_b32 v62, v51 offset:768
	s_waitcnt lgkmcnt(0)
	global_atomic_add_f32 v[12:13], v65, off offset:512
	global_atomic_add_f32 v[14:15], v64, off offset:512
	global_atomic_add_f32 v[16:17], v63, off offset:512
	global_atomic_add_f32 v[18:19], v62, off offset:512
	ds_write_b128 v53, v[82:85]
	ds_read_b32 v61, v51
	ds_read_b32 v60, v51 offset:256
	ds_read_b32 v59, v51 offset:512
	ds_read_b32 v58, v51 offset:768
	s_waitcnt lgkmcnt(0)
	global_atomic_add_f32 v[12:13], v61, off offset:576
	global_atomic_add_f32 v[14:15], v60, off offset:576
	global_atomic_add_f32 v[16:17], v59, off offset:576
	global_atomic_add_f32 v[18:19], v58, off offset:576
	v_lshl_add_u64 v[10:11], v[154:155], 0, v[130:131]
	v_lshl_add_u64 v[12:13], v[10:11], 0, v[2:3]
	v_lshl_add_u64 v[14:15], v[10:11], 0, v[4:5]
	v_lshl_add_u64 v[16:17], v[10:11], 0, v[6:7]
	v_lshl_add_u64 v[18:19], v[10:11], 0, v[8:9]
	ds_write_b128 v53, v[78:81]
	ds_read_b32 v65, v51
	ds_read_b32 v64, v51 offset:256
	ds_read_b32 v63, v51 offset:512
	ds_read_b32 v62, v51 offset:768
	s_waitcnt lgkmcnt(0)
	global_atomic_add_f32 v[12:13], v65, off
	global_atomic_add_f32 v[14:15], v64, off
	global_atomic_add_f32 v[16:17], v63, off
	global_atomic_add_f32 v[18:19], v62, off
	ds_write_b128 v53, v[74:77]
	ds_read_b32 v61, v51
	ds_read_b32 v60, v51 offset:256
	ds_read_b32 v59, v51 offset:512
	ds_read_b32 v58, v51 offset:768
	s_waitcnt lgkmcnt(0)
	global_atomic_add_f32 v[12:13], v61, off offset:64
	global_atomic_add_f32 v[14:15], v60, off offset:64
	global_atomic_add_f32 v[16:17], v59, off offset:64
	global_atomic_add_f32 v[18:19], v58, off offset:64
	ds_write_b128 v53, v[70:73]
	ds_read_b32 v65, v51
	ds_read_b32 v64, v51 offset:256
	ds_read_b32 v63, v51 offset:512
	ds_read_b32 v62, v51 offset:768
	s_waitcnt lgkmcnt(0)
	global_atomic_add_f32 v[12:13], v65, off offset:512
	global_atomic_add_f32 v[14:15], v64, off offset:512
	global_atomic_add_f32 v[16:17], v63, off offset:512
	global_atomic_add_f32 v[18:19], v62, off offset:512
	ds_write_b128 v53, v[66:69]
	ds_read_b32 v61, v51
	ds_read_b32 v60, v51 offset:256
	ds_read_b32 v59, v51 offset:512
	ds_read_b32 v58, v51 offset:768
	s_waitcnt lgkmcnt(0)
	global_atomic_add_f32 v[12:13], v61, off offset:576
	global_atomic_add_f32 v[14:15], v60, off offset:576
	global_atomic_add_f32 v[16:17], v59, off offset:576
	global_atomic_add_f32 v[18:19], v58, off offset:576

;     __device__ __forceinline__ void operator()(const f32x4 (&acc)[2][2][4][2], const Unit& u, int wr, int wc, int fr, int fq) const {
;     ...
;             for (int m = 0; m < 4; ++m) {
;                 const int t = m * 16 + fr;
;                 float* rp = (m < 2 ? dout + (size_t)(ROW_SAMPLE + t) * D : xmeta + (size_t)(t - 32) * D) + col0;
; #pragma unroll
;                 for (int bj = 0; bj < 2; ++bj)
; #pragma unroll
;                     for (int n = 0; n < 2; ++n) { const f32x4 v = acc[0][bj][m][n] * sc[bj][n]; float* p = rp + bj * HALF + n * 16;
;                         if (atomic_tail) { unsafeAtomicAdd(p + 0, v[0]); unsafeAtomicAdd(p + 1, v[1]); unsafeAtomicAdd(p + 2, v[2]); unsafeAtomicAdd(p + 3, v[3]); }
;                         else { const f32x4 x = *(const f32x4*)p; *(f32x4*)p = x + v; } }
;                 asm volatile("" ::: "memory");
.LBB0_2397:
	s_andn2_b64 vcc, exec, s[10:11]
	s_cbranch_vccnz .LBB0_2399
	v_lshlrev_b64 v[130:131], 2, v[192:193]
	v_and_b32_e32 v57, 63, v1
	v_lshrrev_b32_e32 v56, 6, v1
	v_and_b32_e32 v55, 15, v57
	v_lshrrev_b32_e32 v54, 4, v57
	v_lshlrev_b32_e32 v53, 6, v55
	v_lshl_add_u32 v53, v54, 4, v53
	v_lshlrev_b32_e32 v52, 10, v56
	v_add_u32_e32 v52, 0x23000, v52
	v_add_u32_e32 v53, v53, v52
	v_lshl_add_u32 v51, v57, 2, v52
	v_sub_u32_e32 v50, v54, v55
	v_lshlrev_b32_e32 v50, 13, v50
	v_lshl_add_u32 v50, v55, 2, v50
	v_lshlrev_b32_e32 v49, 4, v54
	v_sub_u32_e32 v2, v50, v49
	v_add_u32_e32 v4, 0x8000, v2
	v_add_u32_e32 v6, 0x10000, v2
	v_add_u32_e32 v8, 0x18000, v2
	v_ashrrev_i32_e32 v3, 31, v2
	v_ashrrev_i32_e32 v5, 31, v4
	v_ashrrev_i32_e32 v7, 31, v6
	v_ashrrev_i32_e32 v9, 31, v8
	v_lshl_add_u64 v[10:11], v[178:179], 0, v[130:131]
	v_lshl_add_u64 v[12:13], v[10:11], 0, v[2:3]
	v_lshl_add_u64 v[14:15], v[10:11], 0, v[4:5]
	v_lshl_add_u64 v[16:17], v[10:11], 0, v[6:7]
	v_lshl_add_u64 v[18:19], v[10:11], 0, v[8:9]
	ds_write_b128 v53, v[126:129]
	ds_read_b32 v65, v51
	ds_read_b32 v64, v51 offset:256
	ds_read_b32 v63, v51 offset:512
	ds_read_b32 v62, v51 offset:768
	s_waitcnt lgkmcnt(0)
	global_atomic_add_f32 v[12:13], v65, off
	global_atomic_add_f32 v[14:15], v64, off
	global_atomic_add_f32 v[16:17], v63, off
	global_atomic_add_f32 v[18:19], v62, off
	ds_write_b128 v53, v[122:125]
	ds_read_b32 v61, v51
	ds_read_b32 v60, v51 offset:256
	ds_read_b32 v59, v51 offset:512
	ds_read_b32 v58, v51 offset:768
	s_waitcnt lgkmcnt(0)
	global_atomic_add_f32 v[12:13], v61, off offset:64
	global_atomic_add_f32 v[14:15], v60, off offset:64
	global_atomic_add_f32 v[16:17], v59, off offset:64
	global_atomic_add_f32 v[18:19], v58, off offset:64
	ds_write_b128 v53, v[114:117]
	ds_read_b32 v65, v51
	ds_read_b32 v64, v51 offset:256
	ds_read_b32 v63, v51 offset:512
	ds_read_b32 v62, v51 offset:768
	s_waitcnt lgkmcnt(0)
	global_atomic_add_f32 v[12:13], v65, off offset:512
	global_atomic_add_f32 v[14:15], v64, off offset:512
	global_atomic_add_f32 v[16:17], v63, off offset:512
	global_atomic_add_f32 v[18:19], v62, off offset:512
	ds_write_b128 v53, v[110:113]
	ds_read_b32 v61, v51
	ds_read_b32 v60, v51 offset:256
	ds_read_b32 v59, v51 offset:512
	ds_read_b32 v58, v51 offset:768
	s_waitcnt lgkmcnt(0)
	global_atomic_add_f32 v[12:13], v61, off offset:576
	global_atomic_add_f32 v[14:15], v60, off offset:576
	global_atomic_add_f32 v[16:17], v59, off offset:576
	global_atomic_add_f32 v[18:19], v58, off offset:576
	v_lshl_add_u64 v[10:11], v[180:181], 0, v[130:131]
	v_lshl_add_u64 v[12:13], v[10:11], 0, v[2:3]
	v_lshl_add_u64 v[14:15], v[10:11], 0, v[4:5]
	v_lshl_add_u64 v[16:17], v[10:11], 0, v[6:7]
	v_lshl_add_u64 v[18:19], v[10:11], 0, v[8:9]
	ds_write_b128 v53, v[118:121]
	ds_read_b32 v65, v51
	ds_read_b32 v64, v51 offset:256
	ds_read_b32 v63, v51 offset:512
	ds_read_b32 v62, v51 offset:768
	s_waitcnt lgkmcnt(0)
	global_atomic_add_f32 v[12:13], v65, off
	global_atomic_add_f32 v[14:15], v64, off
	global_atomic_add_f32 v[16:17], v63, off
	global_atomic_add_f32 v[18:19], v62, off
	ds_write_b128 v53, v[106:109]
	ds_read_b32 v61, v51
	ds_read_b32 v60, v51 offset:256
	ds_read_b32 v59, v51 offset:512
	ds_read_b32 v58, v51 offset:768
	s_waitcnt lgkmcnt(0)
	global_atomic_add_f32 v[12:13], v61, off offset:64
	global_atomic_add_f32 v[14:15], v60, off offset:64
	global_atomic_add_f32 v[16:17], v59, off offset:64
	global_atomic_add_f32 v[18:19], v58, off offset:64
	ds_write_b128 v53, v[102:105]
	ds_read_b32 v65, v51
	ds_read_b32 v64, v51 offset:256
	ds_read_b32 v63, v51 offset:512
	ds_read_b32 v62, v51 offset:768
	s_waitcnt lgkmcnt(0)
	global_atomic_add_f32 v[12:13], v65, off offset:512
	global_atomic_add_f32 v[14:15], v64, off offset:512
	global_atomic_add_f32 v[16:17], v63, off offset:512
	global_atomic_add_f32 v[18:19], v62, off offset:512
	ds_write_b128 v53, v[98:101]
	ds_read_b32 v61, v51
	ds_read_b32 v60, v51 offset:256
	ds_read_b32 v59, v51 offset:512
	ds_read_b32 v58, v51 offset:768
	s_waitcnt lgkmcnt(0)
;     __device__ __forceinline__ void operator()(const f32x4 (&acc)[2][2][4][2], const Unit& u, int wr, int wc, int fr, int fq) const {
;     ...
;             for (int m = 0; m < 4; ++m) {
;                 const int t = m * 16 + fr;
;                 float* rp = (m < 2 ? dout + (size_t)(ROW_SAMPLE + t) * D : xmeta + (size_t)(t - 32) * D) + col0;
; #pragma unroll
;                 for (int bj = 0; bj < 2; ++bj)
; #pragma unroll
;                     for (int n = 0; n < 2; ++n) { const f32x4 v = acc[0][bj][m][n] * sc[bj][n]; float* p = rp + bj * HALF + n * 16;
;                         if (atomic_tail) { unsafeAtomicAdd(p + 0, v[0]); unsafeAtomicAdd(p + 1, v[1]); unsafeAtomicAdd(p + 2, v[2]); unsafeAtomicAdd(p + 3, v[3]); }
;                         else { const f32x4 x = *(const f32x4*)p; *(f32x4*)p = x + v; } }
;                 asm volatile("" ::: "memory");
	global_atomic_add_f32 v[12:13], v61, off offset:576
	global_atomic_add_f32 v[14:15], v60, off offset:576
	global_atomic_add_f32 v[16:17], v59, off offset:576
	global_atomic_add_f32 v[18:19], v58, off offset:576
	v_lshl_add_u64 v[10:11], v[182:183], 0, v[130:131]
	v_lshl_add_u64 v[12:13], v[10:11], 0, v[2:3]
	v_lshl_add_u64 v[14:15], v[10:11], 0, v[4:5]
	v_lshl_add_u64 v[16:17], v[10:11], 0, v[6:7]
	v_lshl_add_u64 v[18:19], v[10:11], 0, v[8:9]
	ds_write_b128 v53, v[94:97]
	ds_read_b32 v65, v51
	ds_read_b32 v64, v51 offset:256
	ds_read_b32 v63, v51 offset:512
	ds_read_b32 v62, v51 offset:768
	s_waitcnt lgkmcnt(0)
	global_atomic_add_f32 v[12:13], v65, off
	global_atomic_add_f32 v[14:15], v64, off
	global_atomic_add_f32 v[16:17], v63, off
	global_atomic_add_f32 v[18:19], v62, off
	ds_write_b128 v53, v[90:93]
	ds_read_b32 v61, v51
	ds_read_b32 v60, v51 offset:256
	ds_read_b32 v59, v51 offset:512
	ds_read_b32 v58, v51 offset:768
	s_waitcnt lgkmcnt(0)
	global_atomic_add_f32 v[12:13], v61, off offset:64
	global_atomic_add_f32 v[14:15], v60, off offset:64
	global_atomic_add_f32 v[16:17], v59, off offset:64
	global_atomic_add_f32 v[18:19], v58, off offset:64
	ds_write_b128 v53, v[82:85]
	ds_read_b32 v65, v51
	ds_read_b32 v64, v51 offset:256
	ds_read_b32 v63, v51 offset:512
	ds_read_b32 v62, v51 offset:768
	s_waitcnt lgkmcnt(0)
	global_atomic_add_f32 v[12:13], v65, off offset:512
	global_atomic_add_f32 v[14:15], v64, off offset:512
	global_atomic_add_f32 v[16:17], v63, off offset:512
	global_atomic_add_f32 v[18:19], v62, off offset:512
	ds_write_b128 v53, v[78:81]
	ds_read_b32 v61, v51
	ds_read_b32 v60, v51 offset:256
	ds_read_b32 v59, v51 offset:512
	ds_read_b32 v58, v51 offset:768
	s_waitcnt lgkmcnt(0)
	global_atomic_add_f32 v[12:13], v61, off offset:576
	global_atomic_add_f32 v[14:15], v60, off offset:576
	global_atomic_add_f32 v[16:17], v59, off offset:576
	global_atomic_add_f32 v[18:19], v58, off offset:576
	v_lshl_add_u64 v[10:11], v[184:185], 0, v[130:131]
	v_lshl_add_u64 v[12:13], v[10:11], 0, v[2:3]
	v_lshl_add_u64 v[14:15], v[10:11], 0, v[4:5]
	v_lshl_add_u64 v[16:17], v[10:11], 0, v[6:7]
	v_lshl_add_u64 v[18:19], v[10:11], 0, v[8:9]
	ds_write_b128 v53, v[86:89]
	ds_read_b32 v65, v51
	ds_read_b32 v64, v51 offset:256
	ds_read_b32 v63, v51 offset:512
	ds_read_b32 v62, v51 offset:768
	s_waitcnt lgkmcnt(0)
	global_atomic_add_f32 v[12:13], v65, off
	global_atomic_add_f32 v[14:15], v64, off
	global_atomic_add_f32 v[16:17], v63, off
	global_atomic_add_f32 v[18:19], v62, off
	ds_write_b128 v53, v[74:77]
	ds_read_b32 v61, v51
	ds_read_b32 v60, v51 offset:256
	ds_read_b32 v59, v51 offset:512
	ds_read_b32 v58, v51 offset:768
	s_waitcnt lgkmcnt(0)
	global_atomic_add_f32 v[12:13], v61, off offset:64
	global_atomic_add_f32 v[14:15], v60, off offset:64
	global_atomic_add_f32 v[16:17], v59, off offset:64
	global_atomic_add_f32 v[18:19], v58, off offset:64
	ds_write_b128 v53, v[70:73]
	ds_read_b32 v65, v51
	ds_read_b32 v64, v51 offset:256
	ds_read_b32 v63, v51 offset:512
	ds_read_b32 v62, v51 offset:768
	s_waitcnt lgkmcnt(0)
	global_atomic_add_f32 v[12:13], v65, off offset:512
	global_atomic_add_f32 v[14:15], v64, off offset:512
	global_atomic_add_f32 v[16:17], v63, off offset:512
	global_atomic_add_f32 v[18:19], v62, off offset:512
	ds_write_b128 v53, v[66:69]
	ds_read_b32 v61, v51
	ds_read_b32 v60, v51 offset:256
	ds_read_b32 v59, v51 offset:512
	ds_read_b32 v58, v51 offset:768
	s_waitcnt lgkmcnt(0)
	global_atomic_add_f32 v[12:13], v61, off offset:576
	global_atomic_add_f32 v[14:15], v60, off offset:576
	global_atomic_add_f32 v[16:17], v59, off offset:576
	global_atomic_add_f32 v[18:19], v58, off offset:576
